# attention fast loops: back edge rotated, the step barrier is the loop head and counter/pointer updates sit in front of it
# baseline (speedup 1.0000x reference)
; #define LAS __attribute__((address_space(3)))
; __device__ __forceinline__ s16x4 vtr(LAS unsigned char* p) { return __builtin_bit_cast(s16x4, __builtin_amdgcn_ds_read_tr16_b64_v4i16((LAS s16x4*)p)); }
; template <int DK, int PAR, bool HASNEXT, bool LDK, bool LDV, bool STK> ...
;     ...
;     __builtin_amdgcn_s_setprio(1);
;     if (LDK) { ldk0 = *(const u32x4*)(kg0 + (size_t)(t + 3) * kstep); if (has1) ldk1 = *(const u32x4*)(kg1 + (size_t)(t + 3) * kstep); }
;     if (LDV) ldv = *(const u32x4*)(vg + (size_t)(t + 2) * vstep);
;     bf16x8 kf[A::NDS][2];
;     if (HASNEXT) {
; #pragma unroll
;         for (int ds = 0; ds < A::NDS; ++ds) {
;             kf[ds][0] = *(const LAS bf16x8*)(Kb + aoffk + ds * 32);
;             kf[ds][1] = *(const LAS bf16x8*)(Kb + aoffk + 32 * A::KSTR + ds * 32);
;         }
;     }
;     s16x4 vlo[4][2], vhi[4][2];
; #pragma unroll
;     for (int j = 0; j < 2; ++j) {
;         vlo[j][0] = vtr(Vb + aoffv + j * 16 * A::VSTR); vhi[j][0] = vtr(Vb + aoffv + (j * 16 + 8) * A::VSTR);
;         vlo[j][1] = vtr(Vb + aoffv + j * 16 * A::VSTR + 64); vhi[j][1] = vtr(Vb + aoffv + (j * 16 + 8) * A::VSTR + 64);
;     }
;     if (HASNEXT) {
;         f32x16 z;
; #pragma unroll
;         for (int i = 0; i < 16; ++i) z[i] = 0.f;
; #pragma unroll
;         for (int ds = 0; ds < A::NDS; ++ds) {
;             N0 = __builtin_amdgcn_mfma_f32_32x32x16_bf16(kf[ds][0], qf[ds], ds == 0 ? z : N0, 0, 0, 0);
;             N1 = __builtin_amdgcn_mfma_f32_32x32x16_bf16(kf[ds][1], qf[ds], ds == 0 ? z : N1, 0, 0, 0);
.LBB0_763:
	s_barrier
	s_setprio 1
	v_mfma_f32_32x32x16_bf16 v[32:47], v[216:219], v[120:123], 0
	v_lshl_add_u64 v[66:67], s[50:51], 0, v[164:165]
	v_add_co_u32_e32 v94, vcc, 0x2a5a8000, v66
	v_lshl_add_u64 v[64:65], s[50:51], 0, v[166:167]
	s_nop 0
	v_addc_co_u32_e32 v95, vcc, 0, v67, vcc
	global_load_dwordx4 v[140:143], v[94:95], off
	s_and_saveexec_b64 s[10:11], s[6:7]
	s_cbranch_execz .LBB0_765
	v_add_co_u32_e32 v94, vcc, 0x2a5a8000, v64
	s_nop 1
	v_addc_co_u32_e32 v95, vcc, 0, v65, vcc
	global_load_dwordx4 v[124:127], v[94:95], off

; template <int DK, int PAR, bool HASNEXT, bool LDK, bool LDV, bool STK> ...
;     ...
;             kf[ds][0] = *(const LAS bf16x8*)(Kb + aoffk + ds * 32);
;             kf[ds][1] = *(const LAS bf16x8*)(Kb + aoffk + 32 * A::KSTR + ds * 32);
;         }
;     }
;     s16x4 vlo[4][2], vhi[4][2];
; #pragma unroll
;     for (int j = 0; j < 2; ++j) {
;         vlo[j][0] = vtr(Vb + aoffv + j * 16 * A::VSTR); vhi[j][0] = vtr(Vb + aoffv + (j * 16 + 8) * A::VSTR);
;         vlo[j][1] = vtr(Vb + aoffv + j * 16 * A::VSTR + 64); vhi[j][1] = vtr(Vb + aoffv + (j * 16 + 8) * A::VSTR + 64);
;     }
;     if (HASNEXT) {
;         f32x16 z;
; #pragma unroll
;         for (int i = 0; i < 16; ++i) z[i] = 0.f;
; #pragma unroll
;         for (int ds = 0; ds < A::NDS; ++ds) {
;             N0 = __builtin_amdgcn_mfma_f32_32x32x16_bf16(kf[ds][0], qf[ds], ds == 0 ? z : N0, 0, 0, 0);
;             N1 = __builtin_amdgcn_mfma_f32_32x32x16_bf16(kf[ds][1], qf[ds], ds == 0 ? z : N1, 0, 0, 0);
;         }
;     }
; #pragma unroll
;     for (int i = 0; i < 16; ++i) { l += C0[i]; l += C1[i]; }
;     bf16x8 pb[4];
;     { u32x4 w;
;       w.x = pk2(C0[0], C0[1]); w.y = pk2(C0[2], C0[3]); w.z = pk2(C0[4], C0[5]); w.w = pk2(C0[6], C0[7]); pb[0] = __builtin_bit_cast(bf16x8, w);
;       w.x = pk2(C0[8], C0[9]); w.y = pk2(C0[10], C0[11]); w.z = pk2(C0[12], C0[13]); w.w = pk2(C0[14], C0[15]); pb[1] = __builtin_bit_cast(bf16x8, w);
;       w.x = pk2(C1[0], C1[1]); w.y = pk2(C1[2], C1[3]); w.z = pk2(C1[4], C1[5]); w.w = pk2(C1[6], C1[7]); pb[2] = __builtin_bit_cast(bf16x8, w);
;       w.x = pk2(C1[8], C1[9]); w.y = pk2(C1[10], C1[11]); w.z = pk2(C1[12], C1[13]); w.w = pk2(C1[14], C1[15]); pb[3] = __builtin_bit_cast(bf16x8, w); }
;     if (HASNEXT) {
;         constexpr int VPER = (DK == 64) ? 6 : 4;
; #pragma unroll
;         for (int g = 0; g < 2 * A::NDS; ++g) { __builtin_amdgcn_sched_group_barrier(0x008, 1, 0); __builtin_amdgcn_sched_group_barrier(0x002, VPER, 0); }
;     }
;     asm volatile("" : "+v"(l));
;     __builtin_amdgcn_sched_barrier(0);
; #pragma unroll
;     for (int j = 2; j < 4; ++j) {
;         vlo[j][0] = vtr(Vb + aoffv + j * 16 * A::VSTR); vhi[j][0] = vtr(Vb + aoffv + (j * 16 + 8) * A::VSTR);
;         vlo[j][1] = vtr(Vb + aoffv + j * 16 * A::VSTR + 64); vhi[j][1] = vtr(Vb + aoffv + (j * 16 + 8) * A::VSTR + 64);
;     }
; #pragma unroll
;     for (int j = 0; j < 4; ++j) {
.LBB0_769:
	s_or_b64 exec, exec, s[10:11]
	s_mov_b32 s10, 0x14f48000
	v_mfma_f32_32x32x16_bf16 v[64:79], v[216:219], v[120:123], 0
	v_exp_f32_e32 v57, v42
	v_exp_f32_e32 v190, v58
	v_add_co_u32_e32 v40, vcc, s10, v80
	s_nop 0
	v_addc_co_u32_e32 v41, vcc, 0, v81, vcc
	global_load_dwordx4 v[136:139], v[40:41], off offset:128
	v_add_f32_e32 v48, v96, v94
	v_add_f32_e32 v48, v98, v48
	v_mfma_f32_32x32x16_bf16 v[80:95], v[220:223], v[120:123], 0
	v_exp_f32_e32 v186, v43
	v_exp_f32_e32 v191, v59
	v_add_f32_e32 v40, v99, v48
	v_add_f32_e32 v40, v49, v40
	v_add_f32_e32 v40, v150, v40
	v_add_f32_e32 v40, v151, v40
	v_mfma_f32_32x32x16_bf16 v[64:79], v[224:227], v[116:119], v[64:79]
	v_exp_f32_e32 v192, v44
	v_exp_f32_e32 v193, v60
	v_add_f32_e32 v40, v152, v40
	v_add_f32_e32 v40, v153, v40
	v_add_f32_e32 v40, v154, v40
	v_add_f32_e32 v40, v155, v40
	v_mfma_f32_32x32x16_bf16 v[80:95], v[228:231], v[116:119], v[80:95]
	v_exp_f32_e32 v60, v45
	v_exp_f32_e32 v194, v61
	s_waitcnt vmcnt(3)
	ds_write_b128 v173, v[140:143]
	s_and_saveexec_b64 s[10:11], s[6:7]
	ds_write_b128 v182, v[124:127]
	s_or_b64 exec, exec, s[10:11]
	s_waitcnt vmcnt(2)
	ds_write_b128 v170, v[144:147] offset:26624
	v_add_f32_e32 v40, v52, v40
	v_add_f32_e32 v40, v180, v40
	v_add_f32_e32 v40, v53, v40
	v_add_f32_e32 v40, v183, v40
	v_mfma_f32_32x32x16_bf16 v[64:79], v[236:239], v[112:115], v[64:79]
	v_exp_f32_e32 v61, v46
	v_exp_f32_e32 v62, v62
	v_add_f32_e32 v40, v184, v40
	v_add_f32_e32 v40, v187, v40
	v_add_f32_e32 v40, v185, v40
	v_add_f32_e32 v40, v188, v40
	v_mfma_f32_32x32x16_bf16 v[80:95], v[240:243], v[112:115], v[80:95]
	v_exp_f32_e32 v195, v47
	v_exp_f32_e32 v63, v63
	v_add_f32_e32 v40, v56, v40
	v_add_f32_e32 v40, v189, v40
	v_add_f32_e32 v40, v57, v40
	v_add_f32_e32 v40, v190, v40
	v_mfma_f32_32x32x16_bf16 v[64:79], v[244:247], v[108:111], v[64:79]
	v_add_f32_e32 v40, v186, v40
	v_add_f32_e32 v40, v191, v40
	v_add_f32_e32 v40, v192, v40
	v_add_f32_e32 v44, v193, v40
	v_mfma_f32_32x32x16_bf16 v[80:95], v[248:251], v[108:111], v[80:95]
	v_add_f32_e32 v44, v60, v44
	v_add_f32_e32 v44, v194, v44
	v_add_f32_e32 v44, v61, v44
	v_add_f32_e32 v48, v62, v44
	v_mfma_f32_32x32x16_bf16 v[64:79], v[32:35], v[104:107], v[64:79]
	v_add_f32_e32 v48, v195, v48
	v_add_f32_e32 v48, v63, v48
	v_cvt_pk_bf16_f32 v50, v96, v99
	v_cvt_pk_bf16_f32 v51, v150, v152
	ds_read_b64_tr_b16 v[44:45], v172 offset:38912
	ds_read_b64_tr_b16 v[46:47], v172 offset:40448
	v_mfma_f32_32x32x16_bf16 v[80:95], v[36:39], v[104:107], v[80:95]
	v_cvt_pk_bf16_f32 v52, v154, v52
	v_cvt_pk_bf16_f32 v53, v53, v184
	v_cvt_pk_bf16_f32 v58, v185, v56
	v_cvt_pk_bf16_f32 v59, v57, v186
	ds_read_b64_tr_b16 v[36:37], v172 offset:38976
	ds_read_b64_tr_b16 v[38:39], v172 offset:40512
	ds_read_b64_tr_b16 v[54:55], v172 offset:41984
	v_mfma_f32_32x32x16_bf16 v[64:79], v[196:199], v[100:103], v[64:79]
	v_cvt_pk_bf16_f32 v60, v192, v60
	v_cvt_pk_bf16_f32 v61, v61, v195
	v_cvt_pk_bf16_f32 v184, v98, v49
	v_cvt_pk_bf16_f32 v185, v151, v153
	ds_read_b64_tr_b16 v[56:57], v172 offset:43520
	ds_read_b64_tr_b16 v[40:41], v172 offset:42048
	ds_read_b64_tr_b16 v[42:43], v172 offset:43584
	v_mfma_f32_32x32x16_bf16 v[80:95], v[200:203], v[100:103], v[80:95]
	v_cvt_pk_bf16_f32 v186, v155, v180
	v_cvt_pk_bf16_f32 v187, v183, v187
	v_cvt_pk_bf16_f32 v32, v188, v189
	v_cvt_pk_bf16_f32 v33, v190, v191
	v_cvt_pk_bf16_f32 v34, v193, v194
	v_cvt_pk_bf16_f32 v35, v62, v63
	s_waitcnt lgkmcnt(6)
	v_mfma_f32_32x32x16_bf16 v[16:31], v[44:47], v[50:53], v[16:31]
	v_exp_f32_e32 v189, v67
	v_exp_f32_e32 v188, v68
	v_exp_f32_e32 v190, v69
	v_exp_f32_e32 v192, v70
	s_waitcnt lgkmcnt(4)
	v_mfma_f32_32x32x16_bf16 v[0:15], v[36:39], v[50:53], v[0:15]
	ds_read_b64_tr_b16 v[36:37], v172 offset:45056
	ds_read_b64_tr_b16 v[38:39], v172 offset:46592
	v_exp_f32_e32 v194, v71
	v_exp_f32_e32 v191, v72
	v_exp_f32_e32 v193, v73
	v_exp_f32_e32 v183, v80
	s_waitcnt lgkmcnt(4)
	v_mfma_f32_32x32x16_bf16 v[16:31], v[54:57], v[58:61], v[16:31]
	v_exp_f32_e32 v82, v82
	v_exp_f32_e32 v83, v83
	v_exp_f32_e32 v84, v84
	v_exp_f32_e32 v85, v85
	s_waitcnt lgkmcnt(2)
	v_mfma_f32_32x32x16_bf16 v[0:15], v[40:43], v[58:61], v[0:15]
	ds_read_b64_tr_b16 v[40:41], v172 offset:45120
	ds_read_b64_tr_b16 v[42:43], v172 offset:46656
	ds_read_b128 v[216:219], v181 offset:13312
	ds_read_b128 v[220:223], v181 offset:19968
	ds_read_b128 v[224:227], v181 offset:13344
	v_exp_f32_e32 v86, v86
	v_exp_f32_e32 v87, v87
	v_exp_f32_e32 v72, v88
	v_exp_f32_e32 v73, v89
	s_waitcnt lgkmcnt(5)
	v_mfma_f32_32x32x16_bf16 v[16:31], v[36:39], v[184:187], v[16:31]
	ds_read_b64_tr_b16 v[36:37], v172 offset:48128
	ds_read_b64_tr_b16 v[38:39], v172 offset:49664
	ds_read_b128 v[228:231], v181 offset:20000
	ds_read_b128 v[236:239], v181 offset:13376
	ds_read_b128 v[240:243], v181 offset:20032
	v_exp_f32_e32 v88, v74
	v_exp_f32_e32 v74, v90
	v_exp_f32_e32 v90, v75
	v_exp_f32_e32 v75, v91
	s_waitcnt lgkmcnt(8)
	v_mfma_f32_32x32x16_bf16 v[0:15], v[40:43], v[184:187], v[0:15]
	ds_read_b64_tr_b16 v[40:41], v172 offset:48192
	ds_read_b64_tr_b16 v[42:43], v172 offset:49728
	ds_read_b128 v[244:247], v181 offset:13408
	ds_read_b128 v[248:251], v181 offset:20064
	ds_read_b128 v[68:71], v181 offset:13440
	v_exp_f32_e32 v89, v76
	v_exp_f32_e32 v76, v92
	v_exp_f32_e32 v91, v77
	v_exp_f32_e32 v77, v93
	s_waitcnt lgkmcnt(8)
	v_mfma_f32_32x32x16_bf16 v[16:31], v[36:39], v[32:35], v[16:31]
	ds_read_b128 v[196:199], v181 offset:20096
	ds_read_b128 v[200:203], v181 offset:13472
	ds_read_b128 v[208:211], v181 offset:20128
	v_exp_f32_e32 v92, v78
	v_exp_f32_e32 v78, v94
	v_exp_f32_e32 v93, v79
	v_exp_f32_e32 v79, v95
	s_waitcnt lgkmcnt(6)
	v_mfma_f32_32x32x16_bf16 v[0:15], v[40:43], v[32:35], v[0:15]
	v_exp_f32_e32 v185, v64
	v_exp_f32_e32 v187, v65
	v_exp_f32_e32 v184, v81
	v_exp_f32_e32 v186, v66
	s_setprio 0
	s_add_i32 s12, s12, 2
	s_mov_b64 s[10:11], 0x30000
	v_lshl_add_u64 v[164:165], v[164:165], 0, s[72:73]
	v_lshl_add_u64 v[166:167], v[166:167], 0, s[72:73]
	v_lshl_add_u64 v[168:169], v[168:169], 0, s[10:11]
	s_waitcnt lgkmcnt(0)
	s_cmpk_lt_u32 s12, 0x7e
	s_cbranch_scc1 .LBB0_763
	s_barrier
	s_branch .LBB0_781

; template <int DK, int PAR, bool HASNEXT, bool LDK, bool LDV, bool STK> ...
;     ...
;     if (LDK) { ldk0 = *(const u32x4*)(kg0 + (size_t)(t + 3) * kstep); if (has1) ldk1 = *(const u32x4*)(kg1 + (size_t)(t + 3) * kstep); }
;     if (LDV) ldv = *(const u32x4*)(vg + (size_t)(t + 2) * vstep);
;     bf16x8 kf[A::NDS][2];
;     if (HASNEXT) {
; #pragma unroll
;         for (int ds = 0; ds < A::NDS; ++ds) {
;             kf[ds][0] = *(const LAS bf16x8*)(Kb + aoffk + ds * 32);
;             kf[ds][1] = *(const LAS bf16x8*)(Kb + aoffk + 32 * A::KSTR + ds * 32);
;         }
;     }
;     s16x4 vlo[4][2], vhi[4][2];
; #pragma unroll
;     for (int j = 0; j < 2; ++j) {
;         vlo[j][0] = vtr(Vb + aoffv + j * 16 * A::VSTR); vhi[j][0] = vtr(Vb + aoffv + (j * 16 + 8) * A::VSTR);
;         vlo[j][1] = vtr(Vb + aoffv + j * 16 * A::VSTR + 64); vhi[j][1] = vtr(Vb + aoffv + (j * 16 + 8) * A::VSTR + 64);
;     }
;     if (HASNEXT) {
;         f32x16 z;
; #pragma unroll
;         for (int i = 0; i < 16; ++i) z[i] = 0.f;
; #pragma unroll
;         for (int ds = 0; ds < A::NDS; ++ds) {
;             N0 = __builtin_amdgcn_mfma_f32_32x32x16_bf16(kf[ds][0], qf[ds], ds == 0 ? z : N0, 0, 0, 0);
;             N1 = __builtin_amdgcn_mfma_f32_32x32x16_bf16(kf[ds][1], qf[ds], ds == 0 ? z : N1, 0, 0, 0);
;         }
;     }
; #pragma unroll
;     for (int i = 0; i < 16; ++i) { l += C0[i]; l += C1[i]; }
;     bf16x8 pb[4];
;     { u32x4 w;
;       w.x = pk2(C0[0], C0[1]); w.y = pk2(C0[2], C0[3]); w.z = pk2(C0[4], C0[5]); w.w = pk2(C0[6], C0[7]); pb[0] = __builtin_bit_cast(bf16x8, w);
;       w.x = pk2(C0[8], C0[9]); w.y = pk2(C0[10], C0[11]); w.z = pk2(C0[12], C0[13]); w.w = pk2(C0[14], C0[15]); pb[1] = __builtin_bit_cast(bf16x8, w);
;       w.x = pk2(C1[0], C1[1]); w.y = pk2(C1[2], C1[3]); w.z = pk2(C1[4], C1[5]); w.w = pk2(C1[6], C1[7]); pb[2] = __builtin_bit_cast(bf16x8, w);
;       w.x = pk2(C1[8], C1[9]); w.y = pk2(C1[10], C1[11]); w.z = pk2(C1[12], C1[13]); w.w = pk2(C1[14], C1[15]); pb[3] = __builtin_bit_cast(bf16x8, w); }
;     if (HASNEXT) {
;         constexpr int VPER = (DK == 64) ? 6 : 4;
; #pragma unroll
;         for (int g = 0; g < 2 * A::NDS; ++g) { __builtin_amdgcn_sched_group_barrier(0x008, 1, 0); __builtin_amdgcn_sched_group_barrier(0x002, VPER, 0); }
;     }
;     asm volatile("" : "+v"(l));
;     __builtin_amdgcn_sched_barrier(0);
; #pragma unroll
.LBB0_779:
	s_barrier
	s_setprio 1
	s_mov_b32 s11, 0x23a30000
	ds_read_b64_tr_b16 v[110:111], v96 offset:26624
	v_mfma_f32_32x32x16_bf16 v[48:63], v[216:219], v[76:79], 0
	v_lshl_add_u64 v[126:127], v[122:123], 0, s[8:9]
	v_add_co_u32_e32 v32, vcc, s11, v126
	v_lshl_add_u64 v[128:129], v[124:125], 0, s[8:9]
	s_nop 0
	v_addc_co_u32_e32 v33, vcc, 0, v127, vcc
	s_mov_b32 s11, 0x24aa8000
	global_load_dwordx4 v[88:91], v[32:33], off
	v_add_co_u32_e32 v32, vcc, s11, v128
	ds_read_b64_tr_b16 v[112:113], v96 offset:28160
	s_nop 0
	v_addc_co_u32_e32 v33, vcc, 0, v129, vcc
	global_load_dwordx4 v[92:95], v[32:33], off
	v_mfma_f32_32x32x16_bf16 v[32:47], v[220:223], v[76:79], 0
	v_add_f32_e32 v150, v146, v172
	v_add_f32_e32 v150, v132, v150
	v_add_f32_e32 v150, v148, v150
	v_add_f32_e32 v150, v133, v150
	v_add_f32_e32 v150, v158, v150
	v_add_f32_e32 v150, v134, v150
	ds_read_b64_tr_b16 v[106:107], v96 offset:26688
	v_mfma_f32_32x32x16_bf16 v[32:47], v[224:227], v[72:75], v[32:47]
	v_add_f32_e32 v150, v159, v150
	v_add_f32_e32 v150, v135, v150
	v_add_f32_e32 v150, v160, v150
	v_add_f32_e32 v150, v136, v150
	v_add_f32_e32 v150, v162, v150
	v_add_f32_e32 v150, v137, v150
	ds_read_b64_tr_b16 v[108:109], v96 offset:28224
	v_mfma_f32_32x32x16_bf16 v[48:63], v[228:231], v[72:75], v[48:63]
	s_waitcnt vmcnt(3)
	ds_write_b128 v130, v[80:83] offset:13312
	s_waitcnt vmcnt(2)
	ds_write_b128 v117, v[84:87] offset:38912
	v_add_f32_e32 v150, v164, v150
	v_add_f32_e32 v150, v139, v150
	v_add_f32_e32 v150, v166, v150
	v_add_f32_e32 v150, v141, v150
	v_add_f32_e32 v150, v161, v150
	v_add_f32_e32 v150, v138, v150
	ds_read_b64_tr_b16 v[102:103], v96 offset:29696
	v_mfma_f32_32x32x16_bf16 v[32:47], v[236:239], v[68:71], v[32:47]
	v_add_f32_e32 v150, v163, v150
	v_add_f32_e32 v150, v140, v150
	v_add_f32_e32 v150, v165, v150
	v_add_f32_e32 v150, v142, v150
	v_add_f32_e32 v150, v168, v150
	v_add_f32_e32 v150, v143, v150
	ds_read_b64_tr_b16 v[104:105], v96 offset:31232
	v_mfma_f32_32x32x16_bf16 v[48:63], v[240:243], v[68:71], v[48:63]
	v_add_f32_e32 v150, v167, v150
	v_add_f32_e32 v150, v144, v150
	v_add_f32_e32 v150, v169, v150
	v_add_f32_e32 v150, v145, v150
	ds_read_b64_tr_b16 v[98:99], v96 offset:29760
	ds_read_b64_tr_b16 v[100:101], v96 offset:31296
	v_add_f32_e32 v150, v170, v150
	v_add_f32_e32 v150, v147, v150
	v_mfma_f32_32x32x16_bf16 v[32:47], v[244:247], v[64:67], v[32:47]
	v_add_f32_e32 v150, v171, v150
	v_add_f32_e32 v152, v149, v150
	v_cvt_pk_bf16_f32 v182, v146, v148
	v_cvt_pk_bf16_f32 v183, v158, v159
	v_cvt_pk_bf16_f32 v184, v160, v162
	v_cvt_pk_bf16_f32 v185, v164, v166
	v_mfma_f32_32x32x16_bf16 v[48:63], v[248:251], v[64:67], v[48:63]
	v_cvt_pk_bf16_f32 v158, v161, v163
	v_cvt_pk_bf16_f32 v159, v165, v168
	v_cvt_pk_bf16_f32 v160, v167, v169
	v_cvt_pk_bf16_f32 v161, v170, v171
	v_cvt_pk_bf16_f32 v132, v132, v133
	v_cvt_pk_bf16_f32 v133, v134, v135
	v_cvt_pk_bf16_f32 v134, v136, v137
	v_cvt_pk_bf16_f32 v135, v139, v141
	v_cvt_pk_bf16_f32 v136, v138, v140
	v_cvt_pk_bf16_f32 v137, v142, v143
	v_cvt_pk_bf16_f32 v138, v144, v145
	v_cvt_pk_bf16_f32 v139, v147, v149
	s_waitcnt lgkmcnt(8)
	v_mfma_f32_32x32x16_bf16 v[16:31], v[110:113], v[182:185], v[16:31]
	ds_read_b64_tr_b16 v[110:111], v96 offset:32832
	ds_read_b64_tr_b16 v[112:113], v96 offset:34368
	ds_read_b64_tr_b16 v[140:141], v96 offset:35904
	ds_read_b64_tr_b16 v[142:143], v96 offset:37440
	v_exp_f32_e32 v162, v51
	v_exp_f32_e32 v163, v36
	v_exp_f32_e32 v164, v52
	s_waitcnt lgkmcnt(10)
	v_mfma_f32_32x32x16_bf16 v[0:15], v[106:109], v[182:185], v[0:15]
	ds_read_b64_tr_b16 v[106:107], v96 offset:32768
	ds_read_b64_tr_b16 v[108:109], v96 offset:34304
	v_exp_f32_e32 v165, v37
	v_exp_f32_e32 v166, v53
	v_exp_f32_e32 v167, v38
	v_exp_f32_e32 v168, v54
	v_exp_f32_e32 v169, v39
	s_waitcnt lgkmcnt(8)
	v_mfma_f32_32x32x16_bf16 v[16:31], v[102:105], v[158:161], v[16:31]
	ds_read_b64_tr_b16 v[102:103], v96 offset:35840
	ds_read_b64_tr_b16 v[104:105], v96 offset:37376
	v_exp_f32_e32 v170, v55
	v_exp_f32_e32 v171, v40
	v_exp_f32_e32 v153, v32
	v_exp_f32_e32 v154, v48
	s_waitcnt lgkmcnt(8)
	v_mfma_f32_32x32x16_bf16 v[0:15], v[98:101], v[158:161], v[0:15]
	ds_read_b128 v[216:219], v131 offset:4608
	ds_read_b128 v[220:223], v131
	v_exp_f32_e32 v155, v33
	v_exp_f32_e32 v158, v49
	v_exp_f32_e32 v159, v34
	v_exp_f32_e32 v160, v50
	s_waitcnt lgkmcnt(4)
	v_mfma_f32_32x32x16_bf16 v[16:31], v[106:109], v[132:135], v[16:31]
	ds_read_b128 v[224:227], v131 offset:32
	ds_read_b128 v[228:231], v131 offset:64
	v_exp_f32_e32 v161, v35
	v_exp_f32_e32 v173, v56
	v_exp_f32_e32 v180, v41
	v_exp_f32_e32 v181, v57
	v_mfma_f32_32x32x16_bf16 v[0:15], v[110:113], v[132:135], v[0:15]
	ds_read_b128 v[236:239], v131 offset:96
	ds_read_b128 v[240:243], v131 offset:4640
	v_exp_f32_e32 v182, v42
	v_exp_f32_e32 v183, v58
	v_exp_f32_e32 v184, v43
	v_exp_f32_e32 v185, v59
	s_waitcnt lgkmcnt(6)
	v_mfma_f32_32x32x16_bf16 v[16:31], v[102:105], v[136:139], v[16:31]
	ds_read_b128 v[244:247], v131 offset:4672
	ds_read_b128 v[248:251], v131 offset:4704
	v_exp_f32_e32 v186, v44
	v_exp_f32_e32 v187, v60
	v_exp_f32_e32 v188, v45
	v_exp_f32_e32 v189, v61
	v_mfma_f32_32x32x16_bf16 v[0:15], v[140:143], v[136:139], v[0:15]
	v_exp_f32_e32 v190, v46
	v_exp_f32_e32 v191, v62
	v_exp_f32_e32 v192, v47
	v_exp_f32_e32 v193, v63
	s_setprio 0
	s_waitcnt lgkmcnt(0)
	s_barrier
; template <int DK, int PAR, bool HASNEXT, bool LDK, bool LDV, bool STK> ...
;     ...
; #pragma unroll
;         for (int ds = 0; ds < A::NDS; ++ds) {
;             kf[ds][0] = *(const LAS bf16x8*)(Kb + aoffk + ds * 32);
;             kf[ds][1] = *(const LAS bf16x8*)(Kb + aoffk + 32 * A::KSTR + ds * 32);
;         }
;     }
;     s16x4 vlo[4][2], vhi[4][2];
; #pragma unroll
;     for (int j = 0; j < 2; ++j) {
;         vlo[j][0] = vtr(Vb + aoffv + j * 16 * A::VSTR); vhi[j][0] = vtr(Vb + aoffv + (j * 16 + 8) * A::VSTR);
;         vlo[j][1] = vtr(Vb + aoffv + j * 16 * A::VSTR + 64); vhi[j][1] = vtr(Vb + aoffv + (j * 16 + 8) * A::VSTR + 64);
;     }
;     if (HASNEXT) {
;         f32x16 z;
; #pragma unroll
;         for (int i = 0; i < 16; ++i) z[i] = 0.f;
; #pragma unroll
;         for (int ds = 0; ds < A::NDS; ++ds) {
;             N0 = __builtin_amdgcn_mfma_f32_32x32x16_bf16(kf[ds][0], qf[ds], ds == 0 ? z : N0, 0, 0, 0);
;             N1 = __builtin_amdgcn_mfma_f32_32x32x16_bf16(kf[ds][1], qf[ds], ds == 0 ? z : N1, 0, 0, 0);
;         }
;     }
; #pragma unroll
;     for (int i = 0; i < 16; ++i) { l += C0[i]; l += C1[i]; }
;     bf16x8 pb[4];
;     { u32x4 w;
;       w.x = pk2(C0[0], C0[1]); w.y = pk2(C0[2], C0[3]); w.z = pk2(C0[4], C0[5]); w.w = pk2(C0[6], C0[7]); pb[0] = __builtin_bit_cast(bf16x8, w);
;       w.x = pk2(C0[8], C0[9]); w.y = pk2(C0[10], C0[11]); w.z = pk2(C0[12], C0[13]); w.w = pk2(C0[14], C0[15]); pb[1] = __builtin_bit_cast(bf16x8, w);
;       w.x = pk2(C1[0], C1[1]); w.y = pk2(C1[2], C1[3]); w.z = pk2(C1[4], C1[5]); w.w = pk2(C1[6], C1[7]); pb[2] = __builtin_bit_cast(bf16x8, w);
;       w.x = pk2(C1[8], C1[9]); w.y = pk2(C1[10], C1[11]); w.z = pk2(C1[12], C1[13]); w.w = pk2(C1[14], C1[15]); pb[3] = __builtin_bit_cast(bf16x8, w); }
;     if (HASNEXT) {
;         constexpr int VPER = (DK == 64) ? 6 : 4;
; #pragma unroll
;         for (int g = 0; g < 2 * A::NDS; ++g) { __builtin_amdgcn_sched_group_barrier(0x008, 1, 0); __builtin_amdgcn_sched_group_barrier(0x002, VPER, 0); }
;     }
;     asm volatile("" : "+v"(l));
;     __builtin_amdgcn_sched_barrier(0);
; #pragma unroll
;     for (int j = 2; j < 4; ++j) {
;         vlo[j][0] = vtr(Vb + aoffv + j * 16 * A::VSTR); vhi[j][0] = vtr(Vb + aoffv + (j * 16 + 8) * A::VSTR);
;         vlo[j][1] = vtr(Vb + aoffv + j * 16 * A::VSTR + 64); vhi[j][1] = vtr(Vb + aoffv + (j * 16 + 8) * A::VSTR + 64);
;     }
	s_setprio 1
	s_mov_b32 s11, 0x23a34000
	ds_read_b64_tr_b16 v[110:111], v96 offset:38912
	ds_read_b64_tr_b16 v[112:113], v96 offset:40448
	v_mfma_f32_32x32x16_bf16 v[48:63], v[216:219], v[76:79], 0
	v_add_co_u32_e32 v32, vcc, s11, v126
	s_mov_b32 s11, 0x24aac000
	s_nop 0
	v_addc_co_u32_e32 v33, vcc, 0, v127, vcc
	global_load_dwordx4 v[80:83], v[32:33], off
	v_add_co_u32_e32 v32, vcc, s11, v128
	ds_read_b64_tr_b16 v[106:107], v96 offset:38976
	s_nop 0
	v_addc_co_u32_e32 v33, vcc, 0, v129, vcc
	global_load_dwordx4 v[84:87], v[32:33], off
	v_mfma_f32_32x32x16_bf16 v[32:47], v[220:223], v[76:79], 0
	ds_read_b64_tr_b16 v[108:109], v96 offset:40512
	ds_read_b64_tr_b16 v[102:103], v96 offset:41984
	ds_read_b64_tr_b16 v[104:105], v96 offset:43520
	ds_read_b64_tr_b16 v[98:99], v96 offset:42048
	ds_read_b64_tr_b16 v[100:101], v96 offset:43584
	v_add_f32_e32 v126, v153, v152
	v_add_f32_e32 v126, v154, v126
	v_add_f32_e32 v126, v155, v126
	v_add_f32_e32 v126, v158, v126
	v_add_f32_e32 v126, v159, v126
	v_mfma_f32_32x32x16_bf16 v[32:47], v[224:227], v[72:75], v[32:47]
	v_add_f32_e32 v126, v160, v126
	v_add_f32_e32 v126, v161, v126
	v_add_f32_e32 v126, v162, v126
	v_add_f32_e32 v126, v163, v126
	v_add_f32_e32 v126, v164, v126
	v_mfma_f32_32x32x16_bf16 v[32:47], v[228:231], v[68:71], v[32:47]
	s_waitcnt vmcnt(3)
	ds_write_b128 v130, v[88:91]
	s_waitcnt vmcnt(2)
	ds_write_b128 v117, v[92:95] offset:26624
	v_add_f32_e32 v126, v165, v126
	v_add_f32_e32 v126, v166, v126
	v_add_f32_e32 v126, v167, v126
	v_add_f32_e32 v126, v168, v126
	v_add_f32_e32 v126, v169, v126
	v_mfma_f32_32x32x16_bf16 v[32:47], v[236:239], v[64:67], v[32:47]
	v_add_f32_e32 v126, v170, v126
	v_add_f32_e32 v126, v171, v126
	v_add_f32_e32 v126, v173, v126
	v_add_f32_e32 v126, v180, v126
	v_cvt_pk_bf16_f32 v144, v164, v166
	v_cvt_pk_bf16_f32 v145, v168, v170
	v_cvt_pk_bf16_f32 v136, v186, v188
	v_cvt_pk_bf16_f32 v137, v190, v192
	v_mfma_f32_32x32x16_bf16 v[48:63], v[240:243], v[72:75], v[48:63]
	v_add_f32_e32 v126, v181, v126
	v_add_f32_e32 v126, v182, v126
	v_add_f32_e32 v126, v183, v126
	v_add_f32_e32 v126, v184, v126
	v_cvt_pk_bf16_f32 v134, v171, v180
	v_cvt_pk_bf16_f32 v135, v182, v184
	v_mfma_f32_32x32x16_bf16 v[48:63], v[244:247], v[68:71], v[48:63]
	v_add_f32_e32 v126, v185, v126
	v_add_f32_e32 v126, v186, v126
	v_add_f32_e32 v126, v187, v126
	v_add_f32_e32 v126, v188, v126
	v_cvt_pk_bf16_f32 v142, v154, v158
	v_cvt_pk_bf16_f32 v143, v160, v162
	v_mfma_f32_32x32x16_bf16 v[48:63], v[248:251], v[64:67], v[48:63]
	v_add_f32_e32 v126, v189, v126
	v_add_f32_e32 v126, v190, v126
	v_add_f32_e32 v126, v191, v126
	v_add_f32_e32 v126, v192, v126
	v_add_f32_e32 v172, v193, v126
	v_cvt_pk_bf16_f32 v126, v153, v155
	v_cvt_pk_bf16_f32 v127, v159, v161
	v_cvt_pk_bf16_f32 v128, v163, v165
	v_cvt_pk_bf16_f32 v129, v167, v169
	v_cvt_pk_bf16_f32 v182, v173, v181
	v_cvt_pk_bf16_f32 v183, v183, v185
	v_cvt_pk_bf16_f32 v184, v187, v189
	v_cvt_pk_bf16_f32 v185, v191, v193
	s_waitcnt lgkmcnt(8)
	v_mfma_f32_32x32x16_bf16 v[16:31], v[110:113], v[126:129], v[16:31]
	ds_read_b64_tr_b16 v[110:111], v96 offset:45120
	ds_read_b64_tr_b16 v[112:113], v96 offset:46656
	v_exp_f32_e32 v146, v32
	v_exp_f32_e32 v132, v48
	v_exp_f32_e32 v148, v33
	v_exp_f32_e32 v133, v49
	v_exp_f32_e32 v158, v34
	s_waitcnt lgkmcnt(8)
	v_mfma_f32_32x32x16_bf16 v[0:15], v[106:109], v[126:129], v[0:15]
	ds_read_b64_tr_b16 v[106:107], v96 offset:45056
	ds_read_b64_tr_b16 v[108:109], v96 offset:46592
	ds_read_b64_tr_b16 v[126:127], v96 offset:48192
	ds_read_b64_tr_b16 v[128:129], v96 offset:49728
	v_exp_f32_e32 v159, v35
	v_exp_f32_e32 v160, v36
	v_exp_f32_e32 v162, v37
	s_waitcnt lgkmcnt(10)
	v_mfma_f32_32x32x16_bf16 v[16:31], v[102:105], v[134:137], v[16:31]
	ds_read_b64_tr_b16 v[102:103], v96 offset:48128
	ds_read_b64_tr_b16 v[104:105], v96 offset:49664
	v_exp_f32_e32 v164, v38
	v_exp_f32_e32 v139, v54
	v_exp_f32_e32 v166, v39
	v_exp_f32_e32 v141, v55
	s_waitcnt lgkmcnt(10)
	v_mfma_f32_32x32x16_bf16 v[0:15], v[98:101], v[134:137], v[0:15]
	ds_read_b128 v[216:219], v131 offset:17920
	ds_read_b128 v[220:223], v131 offset:13312
	v_exp_f32_e32 v161, v40
	v_exp_f32_e32 v134, v50
	v_exp_f32_e32 v135, v51
	v_exp_f32_e32 v136, v52
	s_waitcnt lgkmcnt(6)
	v_mfma_f32_32x32x16_bf16 v[16:31], v[106:109], v[142:145], v[16:31]
	ds_read_b128 v[224:227], v131 offset:13344
	ds_read_b128 v[228:231], v131 offset:17952
	v_exp_f32_e32 v137, v53
	v_exp_f32_e32 v138, v56
	v_exp_f32_e32 v163, v41
	v_exp_f32_e32 v140, v57
	v_mfma_f32_32x32x16_bf16 v[0:15], v[110:113], v[142:145], v[0:15]
	ds_read_b128 v[236:239], v131 offset:13376
	ds_read_b128 v[240:243], v131 offset:17984
	v_exp_f32_e32 v165, v42
	v_exp_f32_e32 v168, v43
	v_exp_f32_e32 v167, v44
	v_exp_f32_e32 v169, v45
	s_waitcnt lgkmcnt(6)
	v_mfma_f32_32x32x16_bf16 v[16:31], v[102:105], v[182:185], v[16:31]
	ds_read_b128 v[244:247], v131 offset:13408
	ds_read_b128 v[248:251], v131 offset:18016
	v_exp_f32_e32 v170, v46
	v_exp_f32_e32 v147, v62
	v_exp_f32_e32 v171, v47
	v_exp_f32_e32 v142, v58
	v_mfma_f32_32x32x16_bf16 v[0:15], v[126:129], v[182:185], v[0:15]
	v_exp_f32_e32 v143, v59
	v_exp_f32_e32 v144, v60
	v_exp_f32_e32 v145, v61
	v_exp_f32_e32 v149, v63
	s_setprio 0
	s_add_i32 s10, s10, 2
	v_lshl_add_u64 v[122:123], v[122:123], 0, s[34:35]
	v_lshl_add_u64 v[124:125], v[124:125], 0, s[34:35]
	s_waitcnt lgkmcnt(0)
	s_cmpk_lt_u32 s10, 0x7e
	s_cbranch_scc1 .LBB0_779
	s_barrier
; template <int DK, int PAR, bool HASNEXT, bool LDK, bool LDV, bool STK> ...
;     ...
;     if (LDK) { ldk0 = *(const u32x4*)(kg0 + (size_t)(t + 3) * kstep); if (has1) ldk1 = *(const u32x4*)(kg1 + (size_t)(t + 3) * kstep); }
;     if (LDV) ldv = *(const u32x4*)(vg + (size_t)(t + 2) * vstep);
;     bf16x8 kf[A::NDS][2];
;     if (HASNEXT) {
; #pragma unroll
;         for (int ds = 0; ds < A::NDS; ++ds) {
;             kf[ds][0] = *(const LAS bf16x8*)(Kb + aoffk + ds * 32);
;             kf[ds][1] = *(const LAS bf16x8*)(Kb + aoffk + 32 * A::KSTR + ds * 32);
;         }
;     }
;     s16x4 vlo[4][2], vhi[4][2];
; #pragma unroll
;     for (int j = 0; j < 2; ++j) {
;         vlo[j][0] = vtr(Vb + aoffv + j * 16 * A::VSTR); vhi[j][0] = vtr(Vb + aoffv + (j * 16 + 8) * A::VSTR);
;         vlo[j][1] = vtr(Vb + aoffv + j * 16 * A::VSTR + 64); vhi[j][1] = vtr(Vb + aoffv + (j * 16 + 8) * A::VSTR + 64);
;     }
;     if (HASNEXT) {
;         f32x16 z;
; #pragma unroll
;         for (int i = 0; i < 16; ++i) z[i] = 0.f;
; #pragma unroll
;         for (int ds = 0; ds < A::NDS; ++ds) {
;             N0 = __builtin_amdgcn_mfma_f32_32x32x16_bf16(kf[ds][0], qf[ds], ds == 0 ? z : N0, 0, 0, 0);
;             N1 = __builtin_amdgcn_mfma_f32_32x32x16_bf16(kf[ds][1], qf[ds], ds == 0 ? z : N1, 0, 0, 0);
;         }
;     }
; #pragma unroll
;     for (int i = 0; i < 16; ++i) { l += C0[i]; l += C1[i]; }
;     bf16x8 pb[4];
;     { u32x4 w;
;       w.x = pk2(C0[0], C0[1]); w.y = pk2(C0[2], C0[3]); w.z = pk2(C0[4], C0[5]); w.w = pk2(C0[6], C0[7]); pb[0] = __builtin_bit_cast(bf16x8, w);
;       w.x = pk2(C0[8], C0[9]); w.y = pk2(C0[10], C0[11]); w.z = pk2(C0[12], C0[13]); w.w = pk2(C0[14], C0[15]); pb[1] = __builtin_bit_cast(bf16x8, w);
;       w.x = pk2(C1[0], C1[1]); w.y = pk2(C1[2], C1[3]); w.z = pk2(C1[4], C1[5]); w.w = pk2(C1[6], C1[7]); pb[2] = __builtin_bit_cast(bf16x8, w);
;       w.x = pk2(C1[8], C1[9]); w.y = pk2(C1[10], C1[11]); w.z = pk2(C1[12], C1[13]); w.w = pk2(C1[14], C1[15]); pb[3] = __builtin_bit_cast(bf16x8, w); }
;     if (HASNEXT) {
;         constexpr int VPER = (DK == 64) ? 6 : 4;
; #pragma unroll
;         for (int g = 0; g < 2 * A::NDS; ++g) { __builtin_amdgcn_sched_group_barrier(0x008, 1, 0); __builtin_amdgcn_sched_group_barrier(0x002, VPER, 0); }
;     }
;     asm volatile("" : "+v"(l));
;     __builtin_amdgcn_sched_barrier(0);
; #pragma unroll
	s_waitcnt vmcnt(0)
	ds_read_b128 v[80:83], v130
	s_waitcnt lgkmcnt(0)
	s_setprio 1
	ds_read_b128 v[48:51], v131 offset:17920
	ds_read_b128 v[124:127], v131 offset:17952
	ds_read_b128 v[182:185], v131 offset:13376
	ds_read_b128 v[186:189], v131 offset:17984
	ds_read_b128 v[190:193], v131 offset:13408
	ds_read_b128 v[194:197], v131 offset:18016
	ds_read_b64_tr_b16 v[110:111], v96 offset:26624
	ds_read_b64_tr_b16 v[112:113], v96 offset:28160
	ds_read_b64_tr_b16 v[106:107], v96 offset:26688
	s_waitcnt lgkmcnt(8)
	v_mfma_f32_32x32x16_bf16 v[48:63], v[48:51], v[76:79], 0
	v_add_co_u32_e32 v32, vcc, 0x20c000, v120
	ds_read_b64_tr_b16 v[108:109], v96 offset:28224
	s_nop 0
	v_addc_co_u32_e32 v33, vcc, 0, v121, vcc
	global_load_dwordx4 v[88:91], v[32:33], off
	v_add_co_u32_e32 v32, vcc, 0x208000, v118
	ds_read_b128 v[120:123], v131 offset:13344
	s_nop 0
	v_addc_co_u32_e32 v33, vcc, 0, v119, vcc
	global_load_dwordx4 v[92:95], v[32:33], off
	ds_read_b128 v[32:35], v131 offset:13312
	s_waitcnt lgkmcnt(0)
	v_mfma_f32_32x32x16_bf16 v[32:47], v[32:35], v[76:79], 0
	ds_read_b64_tr_b16 v[102:103], v96 offset:29696
	ds_read_b64_tr_b16 v[104:105], v96 offset:31232
	ds_read_b64_tr_b16 v[98:99], v96 offset:29760
	ds_read_b64_tr_b16 v[100:101], v96 offset:31296
	v_mfma_f32_32x32x16_bf16 v[32:47], v[120:123], v[72:75], v[32:47]
	v_add_f32_e32 v120, v146, v172
	v_add_f32_e32 v120, v132, v120
	v_cvt_pk_bf16_f32 v132, v132, v133
	v_add_f32_e32 v120, v148, v120
	v_add_f32_e32 v120, v133, v120
	v_cvt_pk_bf16_f32 v133, v134, v135
	v_add_f32_e32 v120, v158, v120
	v_add_f32_e32 v120, v134, v120
	v_cvt_pk_bf16_f32 v134, v136, v137
	v_add_f32_e32 v120, v159, v120
	v_add_f32_e32 v120, v135, v120
	v_cvt_pk_bf16_f32 v135, v139, v141
	v_mfma_f32_32x32x16_bf16 v[48:63], v[124:127], v[72:75], v[48:63]
	v_cvt_pk_bf16_f32 v124, v161, v163
	v_cvt_pk_bf16_f32 v125, v165, v168
	v_cvt_pk_bf16_f32 v126, v167, v169
	v_cvt_pk_bf16_f32 v127, v170, v171
	v_add_f32_e32 v120, v160, v120
	v_add_f32_e32 v120, v136, v120
	v_add_f32_e32 v120, v162, v120
	v_add_f32_e32 v120, v137, v120
	v_mfma_f32_32x32x16_bf16 v[32:47], v[182:185], v[68:71], v[32:47]
	v_add_f32_e32 v120, v164, v120
	v_add_f32_e32 v120, v139, v120
	v_add_f32_e32 v120, v166, v120
	v_add_f32_e32 v120, v141, v120
	v_add_f32_e32 v120, v161, v120
	v_add_f32_e32 v120, v138, v120
	v_cvt_pk_bf16_f32 v136, v138, v140
	v_mfma_f32_32x32x16_bf16 v[48:63], v[186:189], v[68:71], v[48:63]
	v_add_f32_e32 v120, v163, v120
	v_add_f32_e32 v120, v140, v120
	v_add_f32_e32 v120, v165, v120
	v_add_f32_e32 v120, v142, v120
	v_add_f32_e32 v120, v168, v120
	v_add_f32_e32 v120, v143, v120
	v_cvt_pk_bf16_f32 v137, v142, v143
	v_mfma_f32_32x32x16_bf16 v[32:47], v[190:193], v[64:67], v[32:47]
	v_add_f32_e32 v120, v167, v120
	v_add_f32_e32 v120, v144, v120
	v_add_f32_e32 v120, v169, v120
	v_add_f32_e32 v120, v145, v120
	v_add_f32_e32 v120, v170, v120
	v_add_f32_e32 v120, v147, v120
	v_cvt_pk_bf16_f32 v138, v144, v145
	v_mfma_f32_32x32x16_bf16 v[48:63], v[194:197], v[64:67], v[48:63]
	v_add_f32_e32 v120, v171, v120
	v_add_f32_e32 v128, v149, v120
	v_cvt_pk_bf16_f32 v120, v146, v148
	v_cvt_pk_bf16_f32 v121, v158, v159
	v_cvt_pk_bf16_f32 v122, v160, v162
	v_cvt_pk_bf16_f32 v123, v164, v166
	v_cvt_pk_bf16_f32 v139, v147, v149
	s_nop 0
	v_mfma_f32_32x32x16_bf16 v[16:31], v[110:113], v[120:123], v[16:31]
	ds_read_b64_tr_b16 v[110:111], v96 offset:32832
	ds_read_b64_tr_b16 v[112:113], v96 offset:34368
	v_exp_f32_e32 v140, v32
	v_exp_f32_e32 v141, v48
	v_exp_f32_e32 v142, v33
	v_exp_f32_e32 v143, v49
	v_exp_f32_e32 v144, v34
	v_mfma_f32_32x32x16_bf16 v[0:15], v[106:109], v[120:123], v[0:15]
	ds_read_b64_tr_b16 v[106:107], v96 offset:32768
	ds_read_b64_tr_b16 v[108:109], v96 offset:34304
	ds_read_b64_tr_b16 v[120:121], v96 offset:35904
	ds_read_b64_tr_b16 v[122:123], v96 offset:37440
	v_exp_f32_e32 v145, v50
	v_exp_f32_e32 v146, v35
	v_exp_f32_e32 v147, v51
	s_waitcnt lgkmcnt(8)
	v_mfma_f32_32x32x16_bf16 v[16:31], v[102:105], v[124:127], v[16:31]
	ds_read_b64_tr_b16 v[102:103], v96 offset:35840
	ds_read_b64_tr_b16 v[104:105], v96 offset:37376
	v_exp_f32_e32 v148, v36
	v_exp_f32_e32 v149, v52
	v_exp_f32_e32 v150, v37
	v_exp_f32_e32 v151, v53
	v_exp_f32_e32 v152, v38
	s_waitcnt lgkmcnt(8)
	v_mfma_f32_32x32x16_bf16 v[0:15], v[98:101], v[124:127], v[0:15]
	v_exp_f32_e32 v153, v54
	v_exp_f32_e32 v154, v39
	v_exp_f32_e32 v155, v55
	v_exp_f32_e32 v158, v40
	v_exp_f32_e32 v159, v58
	v_exp_f32_e32 v160, v43
	v_exp_f32_e32 v161, v59
	s_waitcnt lgkmcnt(4)
	v_mfma_f32_32x32x16_bf16 v[16:31], v[106:109], v[132:135], v[16:31]
	v_exp_f32_e32 v162, v44
	v_exp_f32_e32 v163, v60
	v_exp_f32_e32 v164, v45
	v_exp_f32_e32 v165, v61
	v_exp_f32_e32 v166, v46
	v_exp_f32_e32 v167, v62
	v_exp_f32_e32 v168, v47
	v_mfma_f32_32x32x16_bf16 v[0:15], v[110:113], v[132:135], v[0:15]
	v_exp_f32_e32 v132, v56
	v_exp_f32_e32 v133, v41
	v_exp_f32_e32 v134, v57
	v_exp_f32_e32 v135, v42
	v_exp_f32_e32 v169, v63
	s_waitcnt lgkmcnt(0)
	v_mfma_f32_32x32x16_bf16 v[16:31], v[102:105], v[136:139], v[16:31]
	v_mfma_f32_32x32x16_bf16 v[0:15], v[120:123], v[136:139], v[0:15]
	s_setprio 0
	s_waitcnt vmcnt(3)
	ds_write_b128 v130, v[80:83]
	s_waitcnt vmcnt(2)
	ds_write_b128 v117, v[84:87] offset:38912
	s_waitcnt lgkmcnt(0)
	s_barrier
; template <int DK, int PAR, bool HASNEXT, bool LDK, bool LDV, bool STK> ...
;     ...
;     if (LDK) { ldk0 = *(const u32x4*)(kg0 + (size_t)(t + 3) * kstep); if (has1) ldk1 = *(const u32x4*)(kg1 + (size_t)(t + 3) * kstep); }
;     if (LDV) ldv = *(const u32x4*)(vg + (size_t)(t + 2) * vstep);
;     bf16x8 kf[A::NDS][2];
;     if (HASNEXT) {
; #pragma unroll
;         for (int ds = 0; ds < A::NDS; ++ds) {
;             kf[ds][0] = *(const LAS bf16x8*)(Kb + aoffk + ds * 32);
;             kf[ds][1] = *(const LAS bf16x8*)(Kb + aoffk + 32 * A::KSTR + ds * 32);
;         }
;     }
;     s16x4 vlo[4][2], vhi[4][2];
; #pragma unroll
;     for (int j = 0; j < 2; ++j) {
;         vlo[j][0] = vtr(Vb + aoffv + j * 16 * A::VSTR); vhi[j][0] = vtr(Vb + aoffv + (j * 16 + 8) * A::VSTR);
;         vlo[j][1] = vtr(Vb + aoffv + j * 16 * A::VSTR + 64); vhi[j][1] = vtr(Vb + aoffv + (j * 16 + 8) * A::VSTR + 64);
;     }
;     if (HASNEXT) {
;         f32x16 z;
; #pragma unroll
;         for (int i = 0; i < 16; ++i) z[i] = 0.f;
; #pragma unroll
;         for (int ds = 0; ds < A::NDS; ++ds) {
;             N0 = __builtin_amdgcn_mfma_f32_32x32x16_bf16(kf[ds][0], qf[ds], ds == 0 ? z : N0, 0, 0, 0);
;             N1 = __builtin_amdgcn_mfma_f32_32x32x16_bf16(kf[ds][1], qf[ds], ds == 0 ? z : N1, 0, 0, 0);
;         }
;     }
; #pragma unroll
;     for (int i = 0; i < 16; ++i) { l += C0[i]; l += C1[i]; }
;     bf16x8 pb[4];
;     { u32x4 w;
;       w.x = pk2(C0[0], C0[1]); w.y = pk2(C0[2], C0[3]); w.z = pk2(C0[4], C0[5]); w.w = pk2(C0[6], C0[7]); pb[0] = __builtin_bit_cast(bf16x8, w);
;       w.x = pk2(C0[8], C0[9]); w.y = pk2(C0[10], C0[11]); w.z = pk2(C0[12], C0[13]); w.w = pk2(C0[14], C0[15]); pb[1] = __builtin_bit_cast(bf16x8, w);
;       w.x = pk2(C1[0], C1[1]); w.y = pk2(C1[2], C1[3]); w.z = pk2(C1[4], C1[5]); w.w = pk2(C1[6], C1[7]); pb[2] = __builtin_bit_cast(bf16x8, w);
;       w.x = pk2(C1[8], C1[9]); w.y = pk2(C1[10], C1[11]); w.z = pk2(C1[12], C1[13]); w.w = pk2(C1[14], C1[15]); pb[3] = __builtin_bit_cast(bf16x8, w); }
;     if (HASNEXT) {
;         constexpr int VPER = (DK == 64) ? 6 : 4;
; #pragma unroll
;         for (int g = 0; g < 2 * A::NDS; ++g) { __builtin_amdgcn_sched_group_barrier(0x008, 1, 0); __builtin_amdgcn_sched_group_barrier(0x002, VPER, 0); }
;     }
;     asm volatile("" : "+v"(l));
;     __builtin_amdgcn_sched_barrier(0);
; #pragma unroll
	s_setprio 1
	ds_read_b128 v[32:35], v131
	s_mov_b32 s8, 0x20c000
	ds_read_b128 v[84:87], v131 offset:32
	ds_read_b128 v[98:101], v131 offset:4640
	ds_read_b128 v[102:105], v131 offset:64
	ds_read_b128 v[106:109], v131 offset:4672
	ds_read_b128 v[110:113], v131 offset:96
	ds_read_b64_tr_b16 v[122:123], v96 offset:38912
	ds_read_b64_tr_b16 v[124:125], v96 offset:40448
	s_waitcnt lgkmcnt(7)
	v_mfma_f32_32x32x16_bf16 v[32:47], v[32:35], v[76:79], 0
	v_add_co_u32_e32 v48, vcc, s8, v118
	v_add_f32_e32 v52, v140, v128
	s_nop 0
	v_addc_co_u32_e32 v49, vcc, 0, v119, vcc
	global_load_dwordx4 v[80:83], v[48:49], off
	ds_read_b128 v[48:51], v131 offset:4608
	v_add_f32_e32 v52, v141, v52
	v_add_f32_e32 v52, v142, v52
	v_add_f32_e32 v128, v143, v52
	s_waitcnt lgkmcnt(0)
	v_mfma_f32_32x32x16_bf16 v[48:63], v[48:51], v[76:79], 0
	v_add_f32_e32 v128, v144, v128
	v_add_f32_e32 v128, v145, v128
	v_add_f32_e32 v128, v146, v128
	v_add_f32_e32 v128, v147, v128
	v_add_f32_e32 v128, v148, v128
	v_add_f32_e32 v136, v149, v128
	ds_read_b128 v[118:121], v131 offset:4704
	v_mfma_f32_32x32x16_bf16 v[32:47], v[84:87], v[72:75], v[32:47]
	v_add_f32_e32 v84, v150, v136
	v_add_f32_e32 v84, v151, v84
	v_add_f32_e32 v84, v152, v84
	v_add_f32_e32 v84, v153, v84
	v_add_f32_e32 v84, v154, v84
	v_add_f32_e32 v86, v155, v84
	ds_read_b64_tr_b16 v[126:127], v96 offset:38976
	v_mfma_f32_32x32x16_bf16 v[48:63], v[98:101], v[72:75], v[48:63]
	v_add_f32_e32 v86, v158, v86
	v_add_f32_e32 v86, v132, v86
	v_add_f32_e32 v86, v133, v86
	v_add_f32_e32 v86, v134, v86
	v_add_f32_e32 v86, v135, v86
	v_add_f32_e32 v98, v159, v86
	ds_read_b64_tr_b16 v[128:129], v96 offset:40512
	v_mfma_f32_32x32x16_bf16 v[32:47], v[102:105], v[68:71], v[32:47]
	v_add_f32_e32 v98, v160, v98
	v_add_f32_e32 v98, v161, v98
	v_add_f32_e32 v98, v162, v98
	v_add_f32_e32 v98, v163, v98
	v_add_f32_e32 v98, v164, v98
	v_add_f32_e32 v100, v165, v98
	ds_read_b64_tr_b16 v[84:85], v96 offset:41984
	v_mfma_f32_32x32x16_bf16 v[48:63], v[106:109], v[68:71], v[48:63]
	v_add_f32_e32 v100, v166, v100
	v_add_f32_e32 v100, v167, v100
	v_add_f32_e32 v100, v168, v100
	ds_read_b64_tr_b16 v[86:87], v96 offset:43520
	ds_read_b64_tr_b16 v[98:99], v96 offset:42048
	v_add_f32_e32 v136, v169, v100
	ds_read_b64_tr_b16 v[100:101], v96 offset:43584
	v_cvt_pk_bf16_f32 v102, v140, v142
	v_cvt_pk_bf16_f32 v103, v144, v146
	v_mfma_f32_32x32x16_bf16 v[32:47], v[110:113], v[64:67], v[32:47]
	v_cvt_pk_bf16_f32 v104, v148, v150
	v_cvt_pk_bf16_f32 v105, v152, v154
	v_cvt_pk_bf16_f32 v106, v158, v133
	v_cvt_pk_bf16_f32 v107, v135, v160
	v_cvt_pk_bf16_f32 v108, v162, v164
	v_cvt_pk_bf16_f32 v109, v166, v168
	s_waitcnt lgkmcnt(6)
	v_mfma_f32_32x32x16_bf16 v[48:63], v[118:121], v[64:67], v[48:63]
	v_cvt_pk_bf16_f32 v110, v141, v143
	v_cvt_pk_bf16_f32 v111, v145, v147
	v_cvt_pk_bf16_f32 v112, v149, v151
	v_cvt_pk_bf16_f32 v113, v153, v155
	v_cvt_pk_bf16_f32 v118, v132, v134
	v_cvt_pk_bf16_f32 v119, v159, v161
	v_cvt_pk_bf16_f32 v120, v163, v165
	v_cvt_pk_bf16_f32 v121, v167, v169
	v_mfma_f32_32x32x16_bf16 v[16:31], v[122:125], v[102:105], v[16:31]
	ds_read_b64_tr_b16 v[122:123], v96 offset:45120
	ds_read_b64_tr_b16 v[124:125], v96 offset:46656
	v_exp_f32_e32 v132, v32
	v_exp_f32_e32 v133, v48
	v_exp_f32_e32 v134, v33
	v_exp_f32_e32 v135, v49
	v_exp_f32_e32 v137, v34
	s_waitcnt lgkmcnt(6)
	v_mfma_f32_32x32x16_bf16 v[0:15], v[126:129], v[102:105], v[0:15]
	ds_read_b64_tr_b16 v[102:103], v96 offset:45056
	ds_read_b64_tr_b16 v[104:105], v96 offset:46592
	ds_read_b64_tr_b16 v[126:127], v96 offset:48192
	ds_read_b64_tr_b16 v[128:129], v96 offset:49728
	v_exp_f32_e32 v138, v50
	v_exp_f32_e32 v139, v35
	v_exp_f32_e32 v140, v51
	s_waitcnt lgkmcnt(8)
	v_mfma_f32_32x32x16_bf16 v[16:31], v[84:87], v[106:109], v[16:31]
	ds_read_b64_tr_b16 v[84:85], v96 offset:48128
	ds_read_b64_tr_b16 v[86:87], v96 offset:49664
	v_exp_f32_e32 v141, v36
	v_exp_f32_e32 v142, v52
	v_exp_f32_e32 v143, v37
	v_exp_f32_e32 v144, v53
	v_exp_f32_e32 v145, v38
	s_waitcnt lgkmcnt(8)
	v_mfma_f32_32x32x16_bf16 v[0:15], v[98:101], v[106:109], v[0:15]
	v_exp_f32_e32 v146, v54
	v_exp_f32_e32 v147, v39
	v_exp_f32_e32 v148, v55
	v_exp_f32_e32 v149, v40
	v_exp_f32_e32 v150, v58
	v_exp_f32_e32 v151, v43
	v_exp_f32_e32 v152, v59
	s_waitcnt lgkmcnt(4)
	v_mfma_f32_32x32x16_bf16 v[16:31], v[102:105], v[110:113], v[16:31]
	v_exp_f32_e32 v153, v44
	v_exp_f32_e32 v154, v60
	v_exp_f32_e32 v155, v45
	v_exp_f32_e32 v158, v61
	v_exp_f32_e32 v159, v46
	v_exp_f32_e32 v160, v62
	v_exp_f32_e32 v161, v47
	v_mfma_f32_32x32x16_bf16 v[0:15], v[122:125], v[110:113], v[0:15]
	v_exp_f32_e32 v122, v56
	v_exp_f32_e32 v123, v41
	v_exp_f32_e32 v124, v57
	v_exp_f32_e32 v125, v42
	v_exp_f32_e32 v162, v63
	s_waitcnt lgkmcnt(0)
	v_mfma_f32_32x32x16_bf16 v[16:31], v[84:87], v[118:121], v[16:31]
	v_mfma_f32_32x32x16_bf16 v[0:15], v[126:129], v[118:121], v[0:15]
	s_setprio 0
	s_waitcnt vmcnt(2)
	ds_write_b128 v130, v[88:91] offset:13312
	s_waitcnt vmcnt(1)
	ds_write_b128 v117, v[92:95] offset:26624
	s_waitcnt lgkmcnt(0)
	s_barrier
; template <int DK, int PAR, bool HASNEXT, bool LDK, bool LDV, bool STK> ...
;     ...
;             kf[ds][0] = *(const LAS bf16x8*)(Kb + aoffk + ds * 32);
;             kf[ds][1] = *(const LAS bf16x8*)(Kb + aoffk + 32 * A::KSTR + ds * 32);
;         }
;     }
;     s16x4 vlo[4][2], vhi[4][2];
; #pragma unroll
;     for (int j = 0; j < 2; ++j) {
;         vlo[j][0] = vtr(Vb + aoffv + j * 16 * A::VSTR); vhi[j][0] = vtr(Vb + aoffv + (j * 16 + 8) * A::VSTR);
;         vlo[j][1] = vtr(Vb + aoffv + j * 16 * A::VSTR + 64); vhi[j][1] = vtr(Vb + aoffv + (j * 16 + 8) * A::VSTR + 64);
;     }
;     if (HASNEXT) {
;         f32x16 z;
; #pragma unroll
;         for (int i = 0; i < 16; ++i) z[i] = 0.f;
; #pragma unroll
;         for (int ds = 0; ds < A::NDS; ++ds) {
;             N0 = __builtin_amdgcn_mfma_f32_32x32x16_bf16(kf[ds][0], qf[ds], ds == 0 ? z : N0, 0, 0, 0);
;             N1 = __builtin_amdgcn_mfma_f32_32x32x16_bf16(kf[ds][1], qf[ds], ds == 0 ? z : N1, 0, 0, 0);
;         }
;     }
; #pragma unroll
;     for (int i = 0; i < 16; ++i) { l += C0[i]; l += C1[i]; }
;     bf16x8 pb[4];
;     { u32x4 w;
;       w.x = pk2(C0[0], C0[1]); w.y = pk2(C0[2], C0[3]); w.z = pk2(C0[4], C0[5]); w.w = pk2(C0[6], C0[7]); pb[0] = __builtin_bit_cast(bf16x8, w);
;       w.x = pk2(C0[8], C0[9]); w.y = pk2(C0[10], C0[11]); w.z = pk2(C0[12], C0[13]); w.w = pk2(C0[14], C0[15]); pb[1] = __builtin_bit_cast(bf16x8, w);
;       w.x = pk2(C1[0], C1[1]); w.y = pk2(C1[2], C1[3]); w.z = pk2(C1[4], C1[5]); w.w = pk2(C1[6], C1[7]); pb[2] = __builtin_bit_cast(bf16x8, w);
;       w.x = pk2(C1[8], C1[9]); w.y = pk2(C1[10], C1[11]); w.z = pk2(C1[12], C1[13]); w.w = pk2(C1[14], C1[15]); pb[3] = __builtin_bit_cast(bf16x8, w); }
;     if (HASNEXT) {
;         constexpr int VPER = (DK == 64) ? 6 : 4;
; #pragma unroll
;         for (int g = 0; g < 2 * A::NDS; ++g) { __builtin_amdgcn_sched_group_barrier(0x008, 1, 0); __builtin_amdgcn_sched_group_barrier(0x002, VPER, 0); }
;     }
;     asm volatile("" : "+v"(l));
;     __builtin_amdgcn_sched_barrier(0);
; #pragma unroll
;     for (int j = 2; j < 4; ++j) {
;         vlo[j][0] = vtr(Vb + aoffv + j * 16 * A::VSTR); vhi[j][0] = vtr(Vb + aoffv + (j * 16 + 8) * A::VSTR);
;         vlo[j][1] = vtr(Vb + aoffv + j * 16 * A::VSTR + 64); vhi[j][1] = vtr(Vb + aoffv + (j * 16 + 8) * A::VSTR + 64);
;     }
; #pragma unroll
;     for (int j = 0; j < 4; ++j) {
	s_setprio 1
	ds_read_b128 v[32:35], v131 offset:13312
	ds_read_b128 v[48:51], v131 offset:17920
	ds_read_b128 v[84:87], v131 offset:13344
	ds_read_b128 v[88:91], v131 offset:17952
	ds_read_b128 v[92:95], v131 offset:13376
	ds_read_b128 v[98:101], v131 offset:17984
	ds_read_b128 v[102:105], v131 offset:13408
	ds_read_b128 v[106:109], v131 offset:18016
	ds_read_b64_tr_b16 v[110:111], v96 offset:26624
	s_waitcnt lgkmcnt(8)
	v_mfma_f32_32x32x16_bf16 v[32:47], v[32:35], v[76:79], 0
	v_add_f32_e32 v52, v132, v136
	v_add_f32_e32 v52, v133, v52
	v_add_f32_e32 v52, v134, v52
	v_add_f32_e32 v52, v135, v52
	v_add_f32_e32 v52, v137, v52
	v_add_f32_e32 v118, v138, v52
	ds_read_b64_tr_b16 v[112:113], v96 offset:28160
	s_waitcnt lgkmcnt(8)
	v_mfma_f32_32x32x16_bf16 v[48:63], v[48:51], v[76:79], 0
	v_add_f32_e32 v78, v139, v118
	v_add_f32_e32 v78, v140, v78
	v_add_f32_e32 v78, v141, v78
	v_add_f32_e32 v78, v142, v78
	v_add_f32_e32 v78, v143, v78
	v_add_f32_e32 v118, v144, v78
	ds_read_b64_tr_b16 v[76:77], v96 offset:26688
	s_waitcnt lgkmcnt(8)
	v_mfma_f32_32x32x16_bf16 v[32:47], v[84:87], v[72:75], v[32:47]
	v_add_f32_e32 v84, v145, v118
	v_add_f32_e32 v84, v146, v84
	v_add_f32_e32 v84, v147, v84
	v_add_f32_e32 v84, v148, v84
	v_add_f32_e32 v84, v149, v84
	v_add_f32_e32 v84, v122, v84
	ds_read_b64_tr_b16 v[78:79], v96 offset:28224
	s_waitcnt lgkmcnt(8)
	v_mfma_f32_32x32x16_bf16 v[48:63], v[88:91], v[72:75], v[48:63]
	v_add_f32_e32 v74, v123, v84
	v_add_f32_e32 v74, v124, v74
	v_add_f32_e32 v74, v125, v74
	v_add_f32_e32 v74, v150, v74
	v_add_f32_e32 v74, v151, v74
	v_add_f32_e32 v84, v152, v74
	ds_read_b64_tr_b16 v[72:73], v96 offset:29696
	s_waitcnt lgkmcnt(8)
	v_mfma_f32_32x32x16_bf16 v[32:47], v[92:95], v[68:71], v[32:47]
	v_add_f32_e32 v84, v153, v84
	v_add_f32_e32 v84, v154, v84
	v_add_f32_e32 v84, v155, v84
	v_add_f32_e32 v84, v158, v84
	v_add_f32_e32 v84, v159, v84
	v_add_f32_e32 v84, v160, v84
	ds_read_b64_tr_b16 v[74:75], v96 offset:31232
	s_waitcnt lgkmcnt(8)
	v_mfma_f32_32x32x16_bf16 v[48:63], v[98:101], v[68:71], v[48:63]
	v_add_f32_e32 v70, v161, v84
	ds_read_b64_tr_b16 v[68:69], v96 offset:29760
	v_add_f32_e32 v118, v162, v70
	ds_read_b64_tr_b16 v[70:71], v96 offset:31296
	v_cvt_pk_bf16_f32 v84, v132, v134
	v_cvt_pk_bf16_f32 v85, v137, v139
	v_cvt_pk_bf16_f32 v86, v141, v143
	v_cvt_pk_bf16_f32 v87, v145, v147
	s_waitcnt lgkmcnt(9)
	v_mfma_f32_32x32x16_bf16 v[32:47], v[102:105], v[64:67], v[32:47]
	v_cvt_pk_bf16_f32 v88, v149, v123
	v_cvt_pk_bf16_f32 v89, v125, v151
	v_cvt_pk_bf16_f32 v90, v153, v155
	v_cvt_pk_bf16_f32 v91, v159, v161
	v_cvt_pk_bf16_f32 v92, v133, v135
	v_cvt_pk_bf16_f32 v93, v138, v140
	s_waitcnt lgkmcnt(8)
	v_mfma_f32_32x32x16_bf16 v[48:63], v[106:109], v[64:67], v[48:63]
	v_cvt_pk_bf16_f32 v94, v142, v144
	v_cvt_pk_bf16_f32 v95, v146, v148
	v_cvt_pk_bf16_f32 v64, v122, v124
	v_cvt_pk_bf16_f32 v65, v150, v152
	v_cvt_pk_bf16_f32 v66, v154, v158
	v_cvt_pk_bf16_f32 v67, v160, v162
	s_waitcnt lgkmcnt(6)
	v_mfma_f32_32x32x16_bf16 v[16:31], v[110:113], v[84:87], v[16:31]
	ds_read_b64_tr_b16 v[98:99], v96 offset:35904
	ds_read_b64_tr_b16 v[100:101], v96 offset:37440
	v_exp_f32_e32 v102, v32
	s_nop 0
	v_exp_f32_e32 v103, v48
	v_exp_f32_e32 v48, v33
	v_exp_f32_e32 v63, v63
	s_waitcnt lgkmcnt(6)
	v_mfma_f32_32x32x16_bf16 v[0:15], v[76:79], v[84:87], v[0:15]
	ds_read_b64_tr_b16 v[76:77], v96 offset:32768
	ds_read_b64_tr_b16 v[78:79], v96 offset:34304
	ds_read_b64_tr_b16 v[84:85], v96 offset:32832
	ds_read_b64_tr_b16 v[86:87], v96 offset:34368
	s_waitcnt lgkmcnt(8)
	v_mfma_f32_32x32x16_bf16 v[16:31], v[72:75], v[88:91], v[16:31]
	ds_read_b64_tr_b16 v[72:73], v96 offset:35840
	ds_read_b64_tr_b16 v[74:75], v96 offset:37376
	s_waitcnt lgkmcnt(8)
	v_mfma_f32_32x32x16_bf16 v[0:15], v[68:71], v[88:91], v[0:15]
	v_exp_f32_e32 v68, v49
	v_exp_f32_e32 v49, v34
	v_exp_f32_e32 v69, v50
	v_exp_f32_e32 v50, v35
	v_exp_f32_e32 v70, v51
	v_exp_f32_e32 v51, v36
	v_exp_f32_e32 v71, v52
	s_waitcnt lgkmcnt(4)
	v_mfma_f32_32x32x16_bf16 v[16:31], v[76:79], v[92:95], v[16:31]
	v_exp_f32_e32 v52, v37
	v_exp_f32_e32 v76, v53
	v_exp_f32_e32 v53, v38
	v_exp_f32_e32 v77, v54
	v_exp_f32_e32 v54, v39
	v_exp_f32_e32 v78, v55
	v_exp_f32_e32 v55, v40
	s_waitcnt lgkmcnt(2)
	v_mfma_f32_32x32x16_bf16 v[0:15], v[84:87], v[92:95], v[0:15]
	v_exp_f32_e32 v79, v56
	v_exp_f32_e32 v56, v41
	v_exp_f32_e32 v84, v57
	v_exp_f32_e32 v57, v42
	v_exp_f32_e32 v85, v58
	v_exp_f32_e32 v58, v43
	v_exp_f32_e32 v86, v59
	s_waitcnt lgkmcnt(0)
	v_mfma_f32_32x32x16_bf16 v[16:31], v[72:75], v[64:67], v[16:31]
	v_exp_f32_e32 v59, v44
	v_exp_f32_e32 v72, v60
	v_exp_f32_e32 v60, v45
	v_exp_f32_e32 v73, v61
	v_exp_f32_e32 v61, v46
	v_exp_f32_e32 v74, v62
	v_exp_f32_e32 v62, v47
	v_mfma_f32_32x32x16_bf16 v[0:15], v[98:101], v[64:67], v[0:15]
	s_setprio 0
	s_waitcnt vmcnt(0)
	ds_write_b128 v117, v[80:83] offset:38912
	s_waitcnt lgkmcnt(0)
	s_barrier
; template <int DK, int PAR, bool HASNEXT, bool LDK, bool LDV, bool STK> ...
;     ...
; #pragma unroll
;     for (int i = 0; i < 16; ++i) { l += C0[i]; l += C1[i]; }
;     bf16x8 pb[4];
;     { u32x4 w;
;       w.x = pk2(C0[0], C0[1]); w.y = pk2(C0[2], C0[3]); w.z = pk2(C0[4], C0[5]); w.w = pk2(C0[6], C0[7]); pb[0] = __builtin_bit_cast(bf16x8, w);
;       w.x = pk2(C0[8], C0[9]); w.y = pk2(C0[10], C0[11]); w.z = pk2(C0[12], C0[13]); w.w = pk2(C0[14], C0[15]); pb[1] = __builtin_bit_cast(bf16x8, w);
;       w.x = pk2(C1[0], C1[1]); w.y = pk2(C1[2], C1[3]); w.z = pk2(C1[4], C1[5]); w.w = pk2(C1[6], C1[7]); pb[2] = __builtin_bit_cast(bf16x8, w);
;       w.x = pk2(C1[8], C1[9]); w.y = pk2(C1[10], C1[11]); w.z = pk2(C1[12], C1[13]); w.w = pk2(C1[14], C1[15]); pb[3] = __builtin_bit_cast(bf16x8, w); }
;     if (HASNEXT) {
;         constexpr int VPER = (DK == 64) ? 6 : 4;
; #pragma unroll
;         for (int g = 0; g < 2 * A::NDS; ++g) { __builtin_amdgcn_sched_group_barrier(0x008, 1, 0); __builtin_amdgcn_sched_group_barrier(0x002, VPER, 0); }
;     }
;     asm volatile("" : "+v"(l));
;     __builtin_amdgcn_sched_barrier(0);
; #pragma unroll
;     for (int j = 2; j < 4; ++j) {
;         vlo[j][0] = vtr(Vb + aoffv + j * 16 * A::VSTR); vhi[j][0] = vtr(Vb + aoffv + (j * 16 + 8) * A::VSTR);
;         vlo[j][1] = vtr(Vb + aoffv + j * 16 * A::VSTR + 64); vhi[j][1] = vtr(Vb + aoffv + (j * 16 + 8) * A::VSTR + 64);
;     }
; #pragma unroll
;     for (int j = 0; j < 4; ++j) {
;         const bf16x8 a0 = __builtin_shufflevector(vlo[j][0], vhi[j][0], 0, 1, 2, 3, 4, 5, 6, 7);
;         const bf16x8 a1 = __builtin_shufflevector(vlo[j][1], vhi[j][1], 0, 1, 2, 3, 4, 5, 6, 7);
;         o0 = __builtin_amdgcn_mfma_f32_32x32x16_bf16(a0, pb[j], o0, 0, 0, 0);
;         o1 = __builtin_amdgcn_mfma_f32_32x32x16_bf16(a1, pb[j], o1, 0, 0, 0);
;     }
;     if (HASNEXT) {
; #pragma unroll
;         for (int i = 0; i < 16; ++i) { N0[i] = __builtin_amdgcn_exp2f(N0[i]); N1[i] = __builtin_amdgcn_exp2f(N1[i]); }
; #pragma unroll
;         for (int g = 0; g < 8; ++g) { __builtin_amdgcn_sched_group_barrier(0x008, 1, 0); __builtin_amdgcn_sched_group_barrier(0x002, 4, 0); }
;     }
;     __builtin_amdgcn_sched_barrier(0);
;     __builtin_amdgcn_s_setprio(0);
;     if (STK) { LAS unsigned char* Kn = lds + PAR * A::KBUF; *(LAS u32x4*)(Kn + kl0) = stk0; if (has1) *(LAS u32x4*)(Kn + kl1) = stk1; }
	s_setprio 1
	v_add_f32_e32 v64, v102, v118
	v_add_f32_e32 v64, v103, v64
	v_add_f32_e32 v64, v48, v64
	v_add_f32_e32 v64, v68, v64
	v_add_f32_e32 v64, v49, v64
	v_add_f32_e32 v64, v69, v64
	v_add_f32_e32 v64, v50, v64
	v_add_f32_e32 v64, v70, v64
	v_add_f32_e32 v64, v51, v64
	v_add_f32_e32 v64, v71, v64
	v_add_f32_e32 v64, v52, v64
	v_add_f32_e32 v64, v76, v64
	v_add_f32_e32 v64, v53, v64
	v_add_f32_e32 v64, v77, v64
	v_add_f32_e32 v64, v54, v64
	v_add_f32_e32 v64, v78, v64
	v_add_f32_e32 v64, v55, v64
	v_add_f32_e32 v64, v79, v64
	v_add_f32_e32 v64, v56, v64
	v_add_f32_e32 v64, v84, v64
	v_add_f32_e32 v64, v57, v64
	v_add_f32_e32 v64, v85, v64
	v_add_f32_e32 v64, v58, v64
	v_add_f32_e32 v64, v86, v64
	v_add_f32_e32 v64, v59, v64
	v_add_f32_e32 v64, v72, v64
	v_add_f32_e32 v64, v60, v64
	v_add_f32_e32 v64, v73, v64
	ds_read_b64_tr_b16 v[32:33], v96 offset:38912
	ds_read_b64_tr_b16 v[34:35], v96 offset:40448
	ds_read_b64_tr_b16 v[38:39], v96 offset:40512
	ds_read_b64_tr_b16 v[36:37], v96 offset:38976
	ds_read_b64_tr_b16 v[40:41], v96 offset:41984
	ds_read_b64_tr_b16 v[42:43], v96 offset:43520
	ds_read_b64_tr_b16 v[46:47], v96 offset:43584
	ds_read_b64_tr_b16 v[44:45], v96 offset:42048
	v_add_f32_e32 v64, v61, v64
	v_add_f32_e32 v64, v74, v64
	v_add_f32_e32 v64, v62, v64
	v_add_f32_e32 v64, v63, v64
	v_cvt_pk_bf16_f32 v48, v102, v48
	v_cvt_pk_bf16_f32 v49, v49, v50
	v_cvt_pk_bf16_f32 v50, v51, v52
	v_cvt_pk_bf16_f32 v51, v53, v54
	v_cvt_pk_bf16_f32 v52, v55, v56
	v_cvt_pk_bf16_f32 v53, v57, v58
	v_cvt_pk_bf16_f32 v54, v59, v60
	v_cvt_pk_bf16_f32 v55, v61, v62
	v_cvt_pk_bf16_f32 v56, v103, v68
	v_cvt_pk_bf16_f32 v57, v69, v70
	v_cvt_pk_bf16_f32 v58, v71, v76
	v_cvt_pk_bf16_f32 v59, v77, v78
	v_cvt_pk_bf16_f32 v60, v79, v84
	v_cvt_pk_bf16_f32 v61, v85, v86
	v_cvt_pk_bf16_f32 v62, v72, v73
	v_cvt_pk_bf16_f32 v63, v74, v63
	s_waitcnt lgkmcnt(6)
	v_mfma_f32_32x32x16_bf16 v[16:31], v[32:35], v[48:51], v[16:31]
	ds_read_b64_tr_b16 v[32:33], v96 offset:45056
	ds_read_b64_tr_b16 v[34:35], v96 offset:46592
	s_waitcnt lgkmcnt(6)
	v_mfma_f32_32x32x16_bf16 v[0:15], v[36:39], v[48:51], v[0:15]
	ds_read_b64_tr_b16 v[38:39], v96 offset:46656
	ds_read_b64_tr_b16 v[36:37], v96 offset:45120
	s_waitcnt lgkmcnt(6)
	v_mfma_f32_32x32x16_bf16 v[16:31], v[40:43], v[52:55], v[16:31]
	s_waitcnt lgkmcnt(4)
	v_mfma_f32_32x32x16_bf16 v[0:15], v[44:47], v[52:55], v[0:15]
	s_waitcnt lgkmcnt(2)
	v_mfma_f32_32x32x16_bf16 v[16:31], v[32:35], v[56:59], v[16:31]
	ds_read_b64_tr_b16 v[32:33], v96 offset:48128
	ds_read_b64_tr_b16 v[34:35], v96 offset:49664
	s_waitcnt lgkmcnt(2)
	v_mfma_f32_32x32x16_bf16 v[0:15], v[36:39], v[56:59], v[0:15]
	ds_read_b64_tr_b16 v[38:39], v96 offset:49728
	ds_read_b64_tr_b16 v[36:37], v96 offset:48192
	s_waitcnt lgkmcnt(2)
	v_mfma_f32_32x32x16_bf16 v[16:31], v[32:35], v[60:63], v[16:31]
	s_waitcnt lgkmcnt(0)
	v_mfma_f32_32x32x16_bf16 v[0:15], v[36:39], v[60:63], v[0:15]
	s_setprio 0
	v_mov_b32_e32 v32, v64
	s_nop 1
	v_permlane32_swap_b32_e32 v64, v32
	v_add_f32_e32 v32, v64, v32
	v_div_scale_f32 v33, s[8:9], v32, v32, 1.0
	v_rcp_f32_e32 v34, v33
	v_lshlrev_b32_e32 v96, 1, v116
	s_waitcnt lgkmcnt(0)
	s_barrier
	v_fma_f32 v35, -v33, v34, 1.0
	v_fmac_f32_e32 v34, v35, v34
	v_div_scale_f32 v35, vcc, 1.0, v32, 1.0
	v_mul_f32_e32 v36, v35, v34
	v_fma_f32 v37, -v33, v36, v35
	v_fmac_f32_e32 v36, v37, v34
	v_fma_f32 v33, -v33, v36, v35
	v_div_fmas_f32 v33, v33, v34, v36
	v_div_fixup_f32 v32, v33, v32, 1.0
	v_pk_mul_f32 v[16:17], v[16:17], v[32:33] op_sel_hi:[1,0]
	v_pk_mul_f32 v[18:19], v[18:19], v[32:33] op_sel_hi:[1,0]
	v_pk_mul_f32 v[0:1], v[0:1], v[32:33] op_sel_hi:[1,0]
	v_pk_mul_f32 v[2:3], v[2:3], v[32:33] op_sel_hi:[1,0]
	v_lshlrev_b64 v[34:35], 11, v[114:115]
	v_cvt_pk_bf16_f32 v16, v16, v17
	v_cvt_pk_bf16_f32 v17, v18, v19
	v_pk_mul_f32 v[18:19], v[20:21], v[32:33] op_sel_hi:[1,0]
	v_pk_mul_f32 v[20:21], v[22:23], v[32:33] op_sel_hi:[1,0]
	v_cvt_pk_bf16_f32 v0, v0, v1
	v_cvt_pk_bf16_f32 v1, v2, v3
	v_pk_mul_f32 v[2:3], v[4:5], v[32:33] op_sel_hi:[1,0]
	v_pk_mul_f32 v[4:5], v[6:7], v[32:33] op_sel_hi:[1,0]
	v_lshl_add_u64 v[34:35], s[6:7], 0, v[34:35]
	v_cvt_pk_bf16_f32 v18, v18, v19
	v_cvt_pk_bf16_f32 v19, v20, v21
	v_cvt_pk_bf16_f32 v2, v2, v3
	v_cvt_pk_bf16_f32 v3, v4, v5
	v_lshl_add_u64 v[34:35], v[34:35], 0, v[96:97]
	v_permlane32_swap_b32_e32 v16, v18
	v_permlane32_swap_b32_e32 v17, v19
	v_permlane32_swap_b32_e32 v0, v2
	v_permlane32_swap_b32_e32 v1, v3
	global_store_dwordx4 v[34:35], v[16:19], off
	global_store_dwordx4 v[34:35], v[0:3], off offset:64
	v_pk_mul_f32 v[20:21], v[30:31], v[32:33] op_sel_hi:[1,0]
	v_pk_mul_f32 v[16:17], v[24:25], v[32:33] op_sel_hi:[1,0]
	v_pk_mul_f32 v[18:19], v[26:27], v[32:33] op_sel_hi:[1,0]
	v_pk_mul_f32 v[0:1], v[8:9], v[32:33] op_sel_hi:[1,0]
	v_pk_mul_f32 v[2:3], v[10:11], v[32:33] op_sel_hi:[1,0]
	v_cvt_pk_bf16_f32 v16, v16, v17
	v_cvt_pk_bf16_f32 v17, v18, v19
	v_pk_mul_f32 v[18:19], v[28:29], v[32:33] op_sel_hi:[1,0]
	v_cvt_pk_bf16_f32 v0, v0, v1
	v_cvt_pk_bf16_f32 v1, v2, v3
	v_pk_mul_f32 v[2:3], v[12:13], v[32:33] op_sel_hi:[1,0]
	v_pk_mul_f32 v[4:5], v[14:15], v[32:33] op_sel_hi:[1,0]
	v_cvt_pk_bf16_f32 v18, v18, v19
	v_cvt_pk_bf16_f32 v19, v20, v21
	v_cvt_pk_bf16_f32 v2, v2, v3
	v_cvt_pk_bf16_f32 v3, v4, v5
	v_permlane32_swap_b32_e32 v16, v18
	v_permlane32_swap_b32_e32 v17, v19
	v_permlane32_swap_b32_e32 v0, v2
	v_permlane32_swap_b32_e32 v1, v3
	global_store_dwordx4 v[34:35], v[16:19], off offset:32
	global_store_dwordx4 v[34:35], v[0:3], off offset:96
	s_branch .LBB0_740
